# nt hint on single-use streams while the expert-table slices should stay L2-resident: v-sweep pre1/ple loads + pre-norm stores, LN2 row loads/stores
# baseline (speedup 1.0000x reference)
.Lvsw_skip_gb:
	v_readlane_b32 s100, v252, s39
	v_readlane_b32 s101, v253, s39
	v_ashrrev_i32_e32 v139, 31, v138
	v_lshl_add_u32 v173, s18, 1, v145
	s_lshl_b32 s18, s11, 7
	v_lshlrev_b64 v[138:139], 10, v[138:139]
	v_lshl_add_u64 v[138:139], v[138:139], 0, s[18:19]
	s_lshl_b32 s18, s11, 21
	s_waitcnt lgkmcnt(7)
	v_lshlrev_b32_sdwa v72, v141, v153 dst_sel:DWORD dst_unused:UNUSED_PAD src0_sel:DWORD src1_sel:WORD_0
	s_waitcnt vmcnt(7)
	v_cvt_pk_f32_fp8_e32 v[36:37], v28
	v_cvt_pk_f32_fp8_sdwa v[38:39], v28 src0_sel:WORD_1
	v_cvt_pk_f32_fp8_e32 v[40:41], v29
	v_cvt_pk_f32_fp8_sdwa v[28:29], v29 src0_sel:WORD_1
	v_cvt_pk_f32_fp8_e32 v[42:43], v30
	v_cvt_pk_f32_fp8_sdwa v[44:45], v30 src0_sel:WORD_1
	v_cvt_pk_f32_fp8_e32 v[48:49], v31
	v_cvt_pk_f32_fp8_sdwa v[50:51], v31 src0_sel:WORD_1
	v_lshl_add_u64 v[162:163], v[32:33], 0, s[18:19]
	s_waitcnt vmcnt(6)
	v_cvt_pk_f32_fp8_e32 v[30:31], v20
	v_cvt_pk_f32_fp8_sdwa v[46:47], v20 src0_sel:WORD_1
	v_cvt_pk_f32_fp8_e32 v[52:53], v21
	v_cvt_pk_f32_fp8_sdwa v[54:55], v21 src0_sel:WORD_1
	v_cvt_pk_f32_fp8_e32 v[58:59], v22
	v_cvt_pk_f32_fp8_sdwa v[60:61], v22 src0_sel:WORD_1
	v_cvt_pk_f32_fp8_e32 v[68:69], v23
	v_cvt_pk_f32_fp8_sdwa v[70:71], v23 src0_sel:WORD_1
	v_lshl_add_u32 v154, s39, 8, v77
	v_or_b32_e32 v138, v138, v34
	v_lshl_add_u64 v[156:157], v[162:163], 0, v[72:73]
	s_waitcnt lgkmcnt(6)
	v_lshlrev_b32_sdwa v72, v141, v146 dst_sel:DWORD dst_unused:UNUSED_PAD src0_sel:DWORD src1_sel:WORD_0
	s_waitcnt vmcnt(5)
	v_cvt_pk_f32_fp8_e32 v[20:21], v24
	v_cvt_pk_f32_fp8_sdwa v[22:23], v24 src0_sel:WORD_1
	v_cvt_pk_f32_fp8_e32 v[56:57], v25
	v_cvt_pk_f32_fp8_sdwa v[24:25], v25 src0_sel:WORD_1
	v_cvt_pk_f32_fp8_e32 v[62:63], v26
	v_cvt_pk_f32_fp8_sdwa v[64:65], v26 src0_sel:WORD_1
	v_cvt_pk_f32_fp8_e32 v[78:79], v27
	v_cvt_pk_f32_fp8_sdwa v[80:81], v27 src0_sel:WORD_1
	ds_read_u16 v175, v173
	ds_read_u16 v179, v173 offset:16
	ds_read_u16 v181, v173 offset:32
	ds_read_u16 v183, v173 offset:48
	ds_read_u16 v185, v173 offset:64
	ds_read_u16 v187, v173 offset:80
	ds_read_u16 v189, v173 offset:96
	ds_read_u16 v191, v173 offset:112
	ds_read_u16 v160, v154
	ds_read_u16 v161, v154 offset:16
	ds_read_u16 v169, v154 offset:32
	ds_read_u16 v174, v154 offset:48
	ds_read_u16 v180, v154 offset:64
	ds_read_u16 v182, v154 offset:80
	ds_read_u16 v184, v154 offset:96
	ds_read_u16 v186, v154 offset:112
	ds_read_u16 v153, v173 offset:128
	ds_read_u16 v188, v154 offset:128
	ds_read_u16 v190, v154 offset:144
	ds_read_u16 v192, v154 offset:160
	ds_read_u16 v193, v154 offset:176
	ds_read_u16 v195, v154 offset:192
	ds_read_u16 v197, v154 offset:208
	ds_read_u16 v199, v154 offset:224
	ds_read_u16 v201, v154 offset:240
	v_lshlrev_b64 v[154:155], 2, v[138:139]
	v_lshl_add_u64 v[138:139], v[138:139], 1, s[64:65]
	v_lshl_add_u64 v[158:159], v[162:163], 0, v[72:73]
	s_waitcnt lgkmcnt(14)
	v_lshlrev_b32_sdwa v72, v141, v151 dst_sel:DWORD dst_unused:UNUSED_PAD src0_sel:DWORD src1_sel:WORD_0
	s_waitcnt vmcnt(4)
	v_cvt_pk_f32_fp8_e32 v[26:27], v12
	v_cvt_pk_f32_fp8_sdwa v[66:67], v12 src0_sel:WORD_1
	v_cvt_pk_f32_fp8_e32 v[82:83], v13
	v_cvt_pk_f32_fp8_sdwa v[12:13], v13 src0_sel:WORD_1
	v_cvt_pk_f32_fp8_e32 v[86:87], v14
	v_cvt_pk_f32_fp8_sdwa v[88:89], v14 src0_sel:WORD_1
	v_cvt_pk_f32_fp8_e32 v[92:93], v15
	v_cvt_pk_f32_fp8_sdwa v[94:95], v15 src0_sel:WORD_1
	ds_read_u16 v146, v173 offset:144
	ds_read_u16 v151, v173 offset:160
	v_lshl_add_u64 v[166:167], s[62:63], 0, v[154:155]
	global_load_dword v203, v[138:139], off nt
	v_lshlrev_b32_e32 v168, 16, v160
	v_lshlrev_b32_e32 v170, 16, v161
	v_lshl_add_u64 v[138:139], s[60:61], 0, v[154:155]
	global_load_dwordx4 v[154:157], v[156:157], off
	s_nop 0
	global_load_dwordx4 v[158:161], v[158:159], off
	v_lshl_add_u64 v[204:205], v[162:163], 0, v[72:73]
	v_lshlrev_b32_sdwa v72, v141, v152 dst_sel:DWORD dst_unused:UNUSED_PAD src0_sel:DWORD src1_sel:WORD_0
	v_lshlrev_b32_e32 v172, 16, v169
	v_pk_fma_f32 v[36:37], v[36:37], v[168:169], 0 op_sel_hi:[1,0,0]
	v_pk_fma_f32 v[38:39], v[38:39], v[168:169], 0 op_sel_hi:[1,0,0]
	v_pk_fma_f32 v[40:41], v[40:41], v[168:169], 0 op_sel_hi:[1,0,0]
	v_pk_fma_f32 v[28:29], v[28:29], v[168:169], 0 op_sel_hi:[1,0,0]
	v_pk_fma_f32 v[42:43], v[42:43], v[168:169], 0 op_sel_hi:[1,0,0]
	v_pk_fma_f32 v[44:45], v[44:45], v[168:169], 0 op_sel_hi:[1,0,0]
	v_pk_fma_f32 v[48:49], v[48:49], v[168:169], 0 op_sel_hi:[1,0,0]
	v_pk_fma_f32 v[50:51], v[50:51], v[168:169], 0 op_sel_hi:[1,0,0]
	v_lshl_add_u64 v[168:169], v[162:163], 0, v[72:73]
	v_lshlrev_b32_sdwa v72, v141, v147 dst_sel:DWORD dst_unused:UNUSED_PAD src0_sel:DWORD src1_sel:WORD_0
	s_waitcnt vmcnt(6)
	v_cvt_pk_f32_fp8_e32 v[14:15], v16
	v_cvt_pk_f32_fp8_sdwa v[84:85], v16 src0_sel:WORD_1
	v_cvt_pk_f32_fp8_e32 v[90:91], v17
	v_cvt_pk_f32_fp8_sdwa v[16:17], v17 src0_sel:WORD_1
	v_cvt_pk_f32_fp8_e32 v[96:97], v18
	v_cvt_pk_f32_fp8_sdwa v[98:99], v18 src0_sel:WORD_1
	v_cvt_pk_f32_fp8_e32 v[100:101], v19
	v_cvt_pk_f32_fp8_sdwa v[18:19], v19 src0_sel:WORD_1
	ds_read_u16 v152, v173 offset:176
	ds_read_u16 v147, v173 offset:192
	global_load_dwordx2 v[166:167], v[166:167], off nt
	v_pk_fma_f32 v[30:31], v[30:31], v[170:171], v[36:37] op_sel_hi:[1,0,1]
	v_pk_fma_f32 v[46:47], v[46:47], v[170:171], v[38:39] op_sel_hi:[1,0,1]
	v_pk_fma_f32 v[52:53], v[52:53], v[170:171], v[40:41] op_sel_hi:[1,0,1]
	v_pk_fma_f32 v[28:29], v[54:55], v[170:171], v[28:29] op_sel_hi:[1,0,1]
	v_pk_fma_f32 v[54:55], v[58:59], v[170:171], v[42:43] op_sel_hi:[1,0,1]
	v_pk_fma_f32 v[44:45], v[60:61], v[170:171], v[44:45] op_sel_hi:[1,0,1]
	v_pk_fma_f32 v[48:49], v[68:69], v[170:171], v[48:49] op_sel_hi:[1,0,1]
	v_pk_fma_f32 v[50:51], v[70:71], v[170:171], v[50:51] op_sel_hi:[1,0,1]
	global_load_dwordx4 v[36:39], v[204:205], off
	global_load_dwordx4 v[40:43], v[168:169], off
	v_lshl_add_u64 v[58:59], v[162:163], 0, v[72:73]
	v_lshlrev_b32_sdwa v72, v141, v148 dst_sel:DWORD dst_unused:UNUSED_PAD src0_sel:DWORD src1_sel:WORD_0
	s_waitcnt lgkmcnt(14)
	v_lshlrev_b32_e32 v174, 16, v174
	v_pk_fma_f32 v[20:21], v[20:21], v[172:173], v[30:31] op_sel_hi:[1,0,1]
	v_pk_fma_f32 v[22:23], v[22:23], v[172:173], v[46:47] op_sel_hi:[1,0,1]
	v_pk_fma_f32 v[30:31], v[56:57], v[172:173], v[52:53] op_sel_hi:[1,0,1]
	v_pk_fma_f32 v[24:25], v[24:25], v[172:173], v[28:29] op_sel_hi:[1,0,1]
	v_pk_fma_f32 v[28:29], v[62:63], v[172:173], v[54:55] op_sel_hi:[1,0,1]
	v_pk_fma_f32 v[44:45], v[64:65], v[172:173], v[44:45] op_sel_hi:[1,0,1]
	v_pk_fma_f32 v[46:47], v[78:79], v[172:173], v[48:49] op_sel_hi:[1,0,1]
	v_pk_fma_f32 v[48:49], v[80:81], v[172:173], v[50:51] op_sel_hi:[1,0,1]
	v_lshl_add_u64 v[50:51], v[162:163], 0, v[72:73]
	ds_read_u16 v148, v173 offset:208
	v_lshlrev_b32_sdwa v72, v141, v149 dst_sel:DWORD dst_unused:UNUSED_PAD src0_sel:DWORD src1_sel:WORD_0
	ds_read_u16 v149, v173 offset:224
	v_pk_fma_f32 v[20:21], v[26:27], v[174:175], v[20:21] op_sel_hi:[1,0,1]
	v_pk_fma_f32 v[26:27], v[82:83], v[174:175], v[30:31] op_sel_hi:[1,0,1]
	v_pk_fma_f32 v[12:13], v[12:13], v[174:175], v[24:25] op_sel_hi:[1,0,1]
	v_pk_fma_f32 v[24:25], v[86:87], v[174:175], v[28:29] op_sel_hi:[1,0,1]
	v_pk_fma_f32 v[28:29], v[88:89], v[174:175], v[44:45] op_sel_hi:[1,0,1]
	v_pk_fma_f32 v[30:31], v[92:93], v[174:175], v[46:47] op_sel_hi:[1,0,1]
	v_pk_fma_f32 v[52:53], v[94:95], v[174:175], v[48:49] op_sel_hi:[1,0,1]
	global_load_dwordx4 v[44:47], v[58:59], off
	s_nop 0
	global_load_dwordx4 v[48:51], v[50:51], off
	v_lshlrev_b32_e32 v180, 16, v180
	v_lshl_add_u64 v[54:55], v[162:163], 0, v[72:73]
	v_lshlrev_b32_sdwa v72, v141, v150 dst_sel:DWORD dst_unused:UNUSED_PAD src0_sel:DWORD src1_sel:WORD_0
	ds_read_u16 v150, v173 offset:240
	v_pk_fma_f32 v[12:13], v[16:17], v[180:181], v[12:13] op_sel_hi:[1,0,1]
	v_pk_fma_f32 v[16:17], v[96:97], v[180:181], v[24:25] op_sel_hi:[1,0,1]
	v_pk_fma_f32 v[24:25], v[98:99], v[180:181], v[28:29] op_sel_hi:[1,0,1]
	v_pk_fma_f32 v[18:19], v[18:19], v[180:181], v[52:53] op_sel_hi:[1,0,1]
	v_lshl_add_u64 v[28:29], v[162:163], 0, v[72:73]
	global_load_dwordx4 v[52:55], v[54:55], off
	s_nop 0
	global_load_dwordx4 v[56:59], v[28:29], off
	s_waitcnt vmcnt(12)
	v_cvt_pk_f32_fp8_e32 v[102:103], v4
	v_cvt_pk_f32_fp8_sdwa v[104:105], v4 src0_sel:WORD_1
	v_cvt_pk_f32_fp8_e32 v[106:107], v5
	v_cvt_pk_f32_fp8_sdwa v[4:5], v5 src0_sel:WORD_1
	v_cvt_pk_f32_fp8_e32 v[108:109], v6
	v_cvt_pk_f32_fp8_sdwa v[110:111], v6 src0_sel:WORD_1
	v_cvt_pk_f32_fp8_e32 v[114:115], v7
	v_cvt_pk_f32_fp8_sdwa v[116:117], v7 src0_sel:WORD_1
	s_waitcnt vmcnt(11)
	v_cvt_pk_f32_fp8_e32 v[6:7], v8
	v_cvt_pk_f32_fp8_sdwa v[112:113], v8 src0_sel:WORD_1
	v_cvt_pk_f32_fp8_e32 v[118:119], v9
	v_cvt_pk_f32_fp8_sdwa v[8:9], v9 src0_sel:WORD_1
	v_cvt_pk_f32_fp8_e32 v[120:121], v10
	v_cvt_pk_f32_fp8_sdwa v[122:123], v10 src0_sel:WORD_1
	v_cvt_pk_f32_fp8_e32 v[124:125], v11
	v_cvt_pk_f32_fp8_sdwa v[10:11], v11 src0_sel:WORD_1
	s_waitcnt vmcnt(10)
	v_cvt_pk_f32_fp8_e32 v[126:127], v0
	v_cvt_pk_f32_fp8_sdwa v[128:129], v0 src0_sel:WORD_1
	v_cvt_pk_f32_fp8_e32 v[130:131], v1
	v_cvt_pk_f32_fp8_sdwa v[0:1], v1 src0_sel:WORD_1
	s_and_b32 s18, s3, 0xe00000
	v_pk_fma_f32 v[22:23], v[66:67], v[174:175], v[22:23] op_sel_hi:[1,0,1]
	v_cvt_pk_f32_fp8_e32 v[132:133], v2
	v_cvt_pk_f32_fp8_sdwa v[134:135], v2 src0_sel:WORD_1
	v_cvt_pk_f32_fp8_e32 v[136:137], v3
	v_cvt_pk_f32_fp8_sdwa v[2:3], v3 src0_sel:WORD_1
	v_lshl_add_u64 v[164:165], v[32:33], 0, s[18:19]
	v_lshlrev_b32_e32 v182, 16, v182
	v_pk_fma_f32 v[14:15], v[14:15], v[180:181], v[20:21] op_sel_hi:[1,0,1]
	v_pk_fma_f32 v[20:21], v[84:85], v[180:181], v[22:23] op_sel_hi:[1,0,1]
	v_pk_fma_f32 v[22:23], v[90:91], v[180:181], v[26:27] op_sel_hi:[1,0,1]
	v_pk_fma_f32 v[26:27], v[100:101], v[180:181], v[30:31] op_sel_hi:[1,0,1]
	v_lshlrev_b32_e32 v72, 7, v175
	v_lshlrev_b32_e32 v184, 16, v184
	v_pk_fma_f32 v[4:5], v[4:5], v[182:183], v[12:13] op_sel_hi:[1,0,1]
	v_pk_fma_f32 v[12:13], v[108:109], v[182:183], v[16:17] op_sel_hi:[1,0,1]
	v_pk_fma_f32 v[16:17], v[110:111], v[182:183], v[24:25] op_sel_hi:[1,0,1]
	v_pk_fma_f32 v[24:25], v[114:115], v[182:183], v[26:27] op_sel_hi:[1,0,1]
	v_pk_fma_f32 v[18:19], v[116:117], v[182:183], v[18:19] op_sel_hi:[1,0,1]
	v_lshl_add_u64 v[26:27], v[164:165], 0, v[72:73]
	v_lshlrev_b32_e32 v72, 7, v179
	s_waitcnt lgkmcnt(14)
	v_lshlrev_b32_e32 v186, 16, v186
	v_pk_fma_f32 v[4:5], v[8:9], v[184:185], v[4:5] op_sel_hi:[1,0,1]
	v_pk_fma_f32 v[10:11], v[10:11], v[184:185], v[18:19] op_sel_hi:[1,0,1]
	v_lshl_add_u64 v[18:19], v[164:165], 0, v[72:73]
	v_lshlrev_b32_e32 v72, 7, v181
	v_pk_fma_f32 v[14:15], v[102:103], v[182:183], v[14:15] op_sel_hi:[1,0,1]
	v_pk_fma_f32 v[20:21], v[104:105], v[182:183], v[20:21] op_sel_hi:[1,0,1]
	v_pk_fma_f32 v[22:23], v[106:107], v[182:183], v[22:23] op_sel_hi:[1,0,1]
	v_pk_fma_f32 v[66:67], v[0:1], v[186:187], v[4:5] op_sel_hi:[1,0,1]
	v_lshl_add_u64 v[0:1], v[164:165], 0, v[72:73]
	v_lshlrev_b32_e32 v72, 7, v183
	v_pk_fma_f32 v[6:7], v[6:7], v[184:185], v[14:15] op_sel_hi:[1,0,1]
	v_pk_fma_f32 v[14:15], v[112:113], v[184:185], v[20:21] op_sel_hi:[1,0,1]
	v_pk_fma_f32 v[20:21], v[118:119], v[184:185], v[22:23] op_sel_hi:[1,0,1]
	v_pk_fma_f32 v[8:9], v[120:121], v[184:185], v[12:13] op_sel_hi:[1,0,1]
	v_pk_fma_f32 v[12:13], v[122:123], v[184:185], v[16:17] op_sel_hi:[1,0,1]
	v_pk_fma_f32 v[80:81], v[2:3], v[186:187], v[10:11] op_sel_hi:[1,0,1]
	v_lshl_add_u64 v[2:3], v[164:165], 0, v[72:73]
	v_lshlrev_b32_e32 v72, 7, v185
	v_pk_fma_f32 v[16:17], v[124:125], v[184:185], v[24:25] op_sel_hi:[1,0,1]
	v_pk_fma_f32 v[62:63], v[128:129], v[186:187], v[14:15] op_sel_hi:[1,0,1]
	v_pk_fma_f32 v[64:65], v[130:131], v[186:187], v[20:21] op_sel_hi:[1,0,1]
	v_pk_fma_f32 v[70:71], v[134:135], v[186:187], v[12:13] op_sel_hi:[1,0,1]
	global_load_dwordx4 v[28:31], v[26:27], off
	global_load_dwordx4 v[20:23], v[18:19], off
	s_nop 0
	global_load_dwordx4 v[24:27], v[0:1], off
	global_load_dwordx4 v[12:15], v[2:3], off
	v_lshl_add_u64 v[0:1], v[164:165], 0, v[72:73]
	v_lshlrev_b32_e32 v72, 7, v187
	v_lshl_add_u64 v[2:3], v[164:165], 0, v[72:73]
	v_lshlrev_b32_e32 v72, 7, v189
	v_pk_fma_f32 v[60:61], v[126:127], v[186:187], v[6:7] op_sel_hi:[1,0,1]
	v_pk_fma_f32 v[78:79], v[136:137], v[186:187], v[16:17] op_sel_hi:[1,0,1]
	global_load_dwordx4 v[16:19], v[0:1], off
	global_load_dwordx4 v[4:7], v[2:3], off
	v_lshl_add_u64 v[0:1], v[164:165], 0, v[72:73]
	v_lshlrev_b32_e32 v72, 7, v191
	v_lshl_add_u64 v[2:3], v[164:165], 0, v[72:73]
	v_pk_fma_f32 v[68:69], v[132:133], v[186:187], v[8:9] op_sel_hi:[1,0,1]
	global_load_dwordx4 v[8:11], v[0:1], off
	s_nop 0
	global_load_dwordx4 v[0:3], v[2:3], off
	s_waitcnt vmcnt(16)
	v_cvt_pk_f32_fp8_e32 v[82:83], v154
	v_cvt_pk_f32_fp8_sdwa v[84:85], v154 src0_sel:WORD_1
	v_cvt_pk_f32_fp8_e32 v[86:87], v155
	v_cvt_pk_f32_fp8_sdwa v[88:89], v155 src0_sel:WORD_1
	v_cvt_pk_f32_fp8_e32 v[90:91], v156
	v_cvt_pk_f32_fp8_sdwa v[92:93], v156 src0_sel:WORD_1
	v_cvt_pk_f32_fp8_e32 v[94:95], v157
	v_cvt_pk_f32_fp8_sdwa v[96:97], v157 src0_sel:WORD_1
	s_waitcnt vmcnt(15)
	v_cvt_pk_f32_fp8_e32 v[100:101], v158
	v_cvt_pk_f32_fp8_sdwa v[102:103], v158 src0_sel:WORD_1
	v_cvt_pk_f32_fp8_e32 v[104:105], v159
	v_cvt_pk_f32_fp8_sdwa v[106:107], v159 src0_sel:WORD_1
	v_cvt_pk_f32_fp8_e32 v[108:109], v160
	v_cvt_pk_f32_fp8_sdwa v[110:111], v160 src0_sel:WORD_1
	v_cvt_pk_f32_fp8_e32 v[112:113], v161
	v_cvt_pk_f32_fp8_sdwa v[114:115], v161 src0_sel:WORD_1
	s_waitcnt vmcnt(13)
	v_cvt_pk_f32_fp8_e32 v[116:117], v36
	v_cvt_pk_f32_fp8_sdwa v[118:119], v36 src0_sel:WORD_1
	v_cvt_pk_f32_fp8_e32 v[120:121], v37
	v_cvt_pk_f32_fp8_sdwa v[36:37], v37 src0_sel:WORD_1
	v_cvt_pk_f32_fp8_e32 v[122:123], v38
	v_cvt_pk_f32_fp8_sdwa v[124:125], v38 src0_sel:WORD_1
	v_cvt_pk_f32_fp8_e32 v[126:127], v39
	v_cvt_pk_f32_fp8_sdwa v[38:39], v39 src0_sel:WORD_1
	v_lshlrev_b32_e32 v188, 16, v188
	s_waitcnt vmcnt(12)
	v_cvt_pk_f32_fp8_e32 v[128:129], v40
	v_cvt_pk_f32_fp8_sdwa v[130:131], v40 src0_sel:WORD_1
	v_cvt_pk_f32_fp8_e32 v[132:133], v41
	v_cvt_pk_f32_fp8_sdwa v[40:41], v41 src0_sel:WORD_1
	v_cvt_pk_f32_fp8_e32 v[134:135], v42
	v_cvt_pk_f32_fp8_sdwa v[136:137], v42 src0_sel:WORD_1
	v_cvt_pk_f32_fp8_e32 v[154:155], v43
	v_cvt_pk_f32_fp8_sdwa v[42:43], v43 src0_sel:WORD_1
	s_waitcnt lgkmcnt(13)
	v_lshlrev_b32_e32 v190, 16, v190
	v_pk_fma_f32 v[60:61], v[82:83], v[188:189], v[60:61] op_sel_hi:[1,0,1]
	v_pk_fma_f32 v[62:63], v[84:85], v[188:189], v[62:63] op_sel_hi:[1,0,1]
	v_pk_fma_f32 v[64:65], v[86:87], v[188:189], v[64:65] op_sel_hi:[1,0,1]
	v_pk_fma_f32 v[66:67], v[88:89], v[188:189], v[66:67] op_sel_hi:[1,0,1]
	v_pk_fma_f32 v[68:69], v[90:91], v[188:189], v[68:69] op_sel_hi:[1,0,1]
	v_pk_fma_f32 v[70:71], v[92:93], v[188:189], v[70:71] op_sel_hi:[1,0,1]
	v_pk_fma_f32 v[78:79], v[94:95], v[188:189], v[78:79] op_sel_hi:[1,0,1]
	v_pk_fma_f32 v[80:81], v[96:97], v[188:189], v[80:81] op_sel_hi:[1,0,1]
	s_waitcnt vmcnt(11)
	v_cvt_pk_f32_fp8_e32 v[82:83], v44
	v_cvt_pk_f32_fp8_sdwa v[84:85], v44 src0_sel:WORD_1
	v_cvt_pk_f32_fp8_e32 v[86:87], v45
	v_cvt_pk_f32_fp8_sdwa v[44:45], v45 src0_sel:WORD_1
	v_cvt_pk_f32_fp8_e32 v[88:89], v46
	v_cvt_pk_f32_fp8_sdwa v[90:91], v46 src0_sel:WORD_1
	v_cvt_pk_f32_fp8_e32 v[92:93], v47
	v_cvt_pk_f32_fp8_sdwa v[46:47], v47 src0_sel:WORD_1
	s_waitcnt lgkmcnt(12)
	v_lshlrev_b32_e32 v192, 16, v192
	v_pk_fma_f32 v[60:61], v[100:101], v[190:191], v[60:61] op_sel_hi:[1,0,1]
	v_pk_fma_f32 v[62:63], v[102:103], v[190:191], v[62:63] op_sel_hi:[1,0,1]
	v_pk_fma_f32 v[64:65], v[104:105], v[190:191], v[64:65] op_sel_hi:[1,0,1]
	v_pk_fma_f32 v[66:67], v[106:107], v[190:191], v[66:67] op_sel_hi:[1,0,1]
	v_pk_fma_f32 v[68:69], v[108:109], v[190:191], v[68:69] op_sel_hi:[1,0,1]
	v_pk_fma_f32 v[70:71], v[110:111], v[190:191], v[70:71] op_sel_hi:[1,0,1]
	v_pk_fma_f32 v[78:79], v[112:113], v[190:191], v[78:79] op_sel_hi:[1,0,1]
	v_pk_fma_f32 v[80:81], v[114:115], v[190:191], v[80:81] op_sel_hi:[1,0,1]
	s_waitcnt vmcnt(10)
	v_cvt_pk_f32_fp8_e32 v[94:95], v48
	v_cvt_pk_f32_fp8_sdwa v[96:97], v48 src0_sel:WORD_1
	v_cvt_pk_f32_fp8_e32 v[100:101], v49
	v_cvt_pk_f32_fp8_sdwa v[48:49], v49 src0_sel:WORD_1
	v_cvt_pk_f32_fp8_e32 v[102:103], v50
	v_cvt_pk_f32_fp8_sdwa v[104:105], v50 src0_sel:WORD_1
	v_cvt_pk_f32_fp8_e32 v[106:107], v51
	v_cvt_pk_f32_fp8_sdwa v[50:51], v51 src0_sel:WORD_1
	s_waitcnt lgkmcnt(11)
	v_lshlrev_b32_e32 v194, 16, v193
	v_pk_fma_f32 v[60:61], v[116:117], v[192:193], v[60:61] op_sel_hi:[1,0,1]
	v_pk_fma_f32 v[62:63], v[118:119], v[192:193], v[62:63] op_sel_hi:[1,0,1]
	v_pk_fma_f32 v[64:65], v[120:121], v[192:193], v[64:65] op_sel_hi:[1,0,1]
	v_pk_fma_f32 v[36:37], v[36:37], v[192:193], v[66:67] op_sel_hi:[1,0,1]
	v_pk_fma_f32 v[66:67], v[122:123], v[192:193], v[68:69] op_sel_hi:[1,0,1]
	v_pk_fma_f32 v[68:69], v[124:125], v[192:193], v[70:71] op_sel_hi:[1,0,1]
	v_pk_fma_f32 v[70:71], v[126:127], v[192:193], v[78:79] op_sel_hi:[1,0,1]
	v_pk_fma_f32 v[38:39], v[38:39], v[192:193], v[80:81] op_sel_hi:[1,0,1]
	s_waitcnt vmcnt(9)
	v_cvt_pk_f32_fp8_e32 v[78:79], v52
	v_cvt_pk_f32_fp8_sdwa v[80:81], v52 src0_sel:WORD_1
	v_cvt_pk_f32_fp8_e32 v[108:109], v53
	v_cvt_pk_f32_fp8_sdwa v[52:53], v53 src0_sel:WORD_1
	v_cvt_pk_f32_fp8_e32 v[110:111], v54
	v_cvt_pk_f32_fp8_sdwa v[112:113], v54 src0_sel:WORD_1
	v_cvt_pk_f32_fp8_e32 v[114:115], v55
	v_cvt_pk_f32_fp8_sdwa v[54:55], v55 src0_sel:WORD_1
	s_waitcnt lgkmcnt(10)
	v_lshlrev_b32_e32 v196, 16, v195
	v_pk_fma_f32 v[60:61], v[128:129], v[194:195], v[60:61] op_sel_hi:[1,0,1]
	v_pk_fma_f32 v[62:63], v[130:131], v[194:195], v[62:63] op_sel_hi:[1,0,1]
	v_pk_fma_f32 v[64:65], v[132:133], v[194:195], v[64:65] op_sel_hi:[1,0,1]
	v_pk_fma_f32 v[36:37], v[40:41], v[194:195], v[36:37] op_sel_hi:[1,0,1]
	v_pk_fma_f32 v[40:41], v[134:135], v[194:195], v[66:67] op_sel_hi:[1,0,1]
	v_pk_fma_f32 v[66:67], v[136:137], v[194:195], v[68:69] op_sel_hi:[1,0,1]
	v_pk_fma_f32 v[68:69], v[154:155], v[194:195], v[70:71] op_sel_hi:[1,0,1]
	v_pk_fma_f32 v[38:39], v[42:43], v[194:195], v[38:39] op_sel_hi:[1,0,1]
	s_waitcnt vmcnt(8)
	v_cvt_pk_f32_fp8_e32 v[42:43], v56
	v_cvt_pk_f32_fp8_sdwa v[70:71], v56 src0_sel:WORD_1
	v_cvt_pk_f32_fp8_e32 v[116:117], v57
	v_cvt_pk_f32_fp8_sdwa v[56:57], v57 src0_sel:WORD_1
	v_cvt_pk_f32_fp8_e32 v[118:119], v58
	v_cvt_pk_f32_fp8_sdwa v[120:121], v58 src0_sel:WORD_1
	v_cvt_pk_f32_fp8_e32 v[122:123], v59
	v_cvt_pk_f32_fp8_sdwa v[58:59], v59 src0_sel:WORD_1
	s_waitcnt lgkmcnt(9)
	v_lshlrev_b32_e32 v198, 16, v197
	v_pk_fma_f32 v[60:61], v[82:83], v[196:197], v[60:61] op_sel_hi:[1,0,1]
	v_pk_fma_f32 v[62:63], v[84:85], v[196:197], v[62:63] op_sel_hi:[1,0,1]
	v_pk_fma_f32 v[64:65], v[86:87], v[196:197], v[64:65] op_sel_hi:[1,0,1]
	v_pk_fma_f32 v[36:37], v[44:45], v[196:197], v[36:37] op_sel_hi:[1,0,1]
	v_pk_fma_f32 v[40:41], v[88:89], v[196:197], v[40:41] op_sel_hi:[1,0,1]
	v_pk_fma_f32 v[44:45], v[90:91], v[196:197], v[66:67] op_sel_hi:[1,0,1]
	v_pk_fma_f32 v[66:67], v[92:93], v[196:197], v[68:69] op_sel_hi:[1,0,1]
	v_pk_fma_f32 v[38:39], v[46:47], v[196:197], v[38:39] op_sel_hi:[1,0,1]
	s_waitcnt lgkmcnt(8)
	v_lshlrev_b32_e32 v200, 16, v199
	v_pk_fma_f32 v[46:47], v[94:95], v[198:199], v[60:61] op_sel_hi:[1,0,1]
	v_pk_fma_f32 v[60:61], v[96:97], v[198:199], v[62:63] op_sel_hi:[1,0,1]
	v_pk_fma_f32 v[62:63], v[100:101], v[198:199], v[64:65] op_sel_hi:[1,0,1]
	v_pk_fma_f32 v[36:37], v[48:49], v[198:199], v[36:37] op_sel_hi:[1,0,1]
	v_pk_fma_f32 v[40:41], v[102:103], v[198:199], v[40:41] op_sel_hi:[1,0,1]
	v_pk_fma_f32 v[44:45], v[104:105], v[198:199], v[44:45] op_sel_hi:[1,0,1]
	v_pk_fma_f32 v[48:49], v[106:107], v[198:199], v[66:67] op_sel_hi:[1,0,1]
	v_pk_fma_f32 v[38:39], v[50:51], v[198:199], v[38:39] op_sel_hi:[1,0,1]
	s_waitcnt lgkmcnt(7)
	v_lshlrev_b32_e32 v202, 16, v201
	v_pk_fma_f32 v[46:47], v[78:79], v[200:201], v[46:47] op_sel_hi:[1,0,1]
	v_pk_fma_f32 v[50:51], v[80:81], v[200:201], v[60:61] op_sel_hi:[1,0,1]
	v_pk_fma_f32 v[60:61], v[108:109], v[200:201], v[62:63] op_sel_hi:[1,0,1]
	v_pk_fma_f32 v[36:37], v[52:53], v[200:201], v[36:37] op_sel_hi:[1,0,1]
	v_pk_fma_f32 v[40:41], v[110:111], v[200:201], v[40:41] op_sel_hi:[1,0,1]
	v_pk_fma_f32 v[44:45], v[112:113], v[200:201], v[44:45] op_sel_hi:[1,0,1]
	v_pk_fma_f32 v[48:49], v[114:115], v[200:201], v[48:49] op_sel_hi:[1,0,1]
	v_pk_fma_f32 v[38:39], v[54:55], v[200:201], v[38:39] op_sel_hi:[1,0,1]
	v_pk_fma_f32 v[42:43], v[42:43], v[202:203], v[46:47] op_sel_hi:[1,0,1]
	v_pk_fma_f32 v[46:47], v[70:71], v[202:203], v[50:51] op_sel_hi:[1,0,1]
	v_pk_fma_f32 v[50:51], v[116:117], v[202:203], v[60:61] op_sel_hi:[1,0,1]
	v_pk_fma_f32 v[36:37], v[56:57], v[202:203], v[36:37] op_sel_hi:[1,0,1]
	v_pk_fma_f32 v[40:41], v[118:119], v[202:203], v[40:41] op_sel_hi:[1,0,1]
	v_pk_fma_f32 v[44:45], v[120:121], v[202:203], v[44:45] op_sel_hi:[1,0,1]
	v_pk_fma_f32 v[48:49], v[122:123], v[202:203], v[48:49] op_sel_hi:[1,0,1]
	v_pk_fma_f32 v[38:39], v[58:59], v[202:203], v[38:39] op_sel_hi:[1,0,1]
	v_cndmask_b32_e64 v52, v42, v40, s[4:5]
	v_cndmask_b32_e64 v53, v43, v41, s[4:5]
	v_cndmask_b32_e64 v41, v41, v43, s[4:5]
	v_cndmask_b32_e64 v40, v40, v42, s[4:5]
	v_cndmask_b32_e64 v54, v46, v44, s[4:5]
	v_cndmask_b32_e64 v55, v47, v45, s[4:5]
	v_cndmask_b32_e64 v43, v45, v47, s[4:5]
	v_cndmask_b32_e64 v42, v44, v46, s[4:5]
	v_cndmask_b32_e64 v56, v50, v48, s[4:5]
	v_cndmask_b32_e64 v57, v51, v49, s[4:5]
	v_cndmask_b32_e64 v45, v49, v51, s[4:5]
	v_cndmask_b32_e64 v44, v48, v50, s[4:5]
	v_cndmask_b32_e64 v50, v36, v38, s[4:5]
	v_cndmask_b32_e64 v51, v37, v39, s[4:5]
	v_cndmask_b32_e64 v37, v39, v37, s[4:5]
	v_cndmask_b32_e64 v36, v38, v36, s[4:5]
	ds_bpermute_b32 v38, v35, v52
	ds_bpermute_b32 v39, v35, v53
	ds_bpermute_b32 v46, v35, v54
	ds_bpermute_b32 v47, v35, v55
	ds_bpermute_b32 v48, v35, v56
	ds_bpermute_b32 v49, v35, v57
	ds_bpermute_b32 v50, v35, v50
	ds_bpermute_b32 v51, v35, v51
	s_waitcnt lgkmcnt(6)
	v_pk_add_f32 v[38:39], v[40:41], v[38:39]
	s_waitcnt lgkmcnt(4)
	v_pk_add_f32 v[40:41], v[42:43], v[46:47]
	s_waitcnt lgkmcnt(2)
	v_pk_add_f32 v[42:43], v[44:45], v[48:49]
	v_lshlrev_b32_e32 v98, 16, v203
	s_waitcnt lgkmcnt(0)
	v_pk_add_f32 v[36:37], v[36:37], v[50:51]
	v_cndmask_b32_e32 v44, v38, v42, vcc
	v_cndmask_b32_e32 v45, v39, v43, vcc
	v_cndmask_b32_e32 v39, v43, v39, vcc
	v_cndmask_b32_e32 v38, v42, v38, vcc
	v_cndmask_b32_e32 v42, v40, v36, vcc
	v_cndmask_b32_e32 v43, v41, v37, vcc
	v_cndmask_b32_e32 v37, v37, v41, vcc
	v_cndmask_b32_e32 v36, v36, v40, vcc
	ds_bpermute_b32 v40, v144, v44
	ds_bpermute_b32 v41, v144, v45
	ds_bpermute_b32 v42, v144, v42
	ds_bpermute_b32 v43, v144, v43
	v_and_b32_e32 v99, 0xffff0000, v203
	s_add_i32 s7, s41, 1
	s_waitcnt lgkmcnt(2)
	v_pk_add_f32 v[38:39], v[38:39], v[40:41]
	s_addk_i32 s6, 0x80
	s_waitcnt lgkmcnt(0)
	v_pk_add_f32 v[36:37], v[36:37], v[42:43]
	s_add_i32 s3, s3, 0x10000
	v_cndmask_b32_e64 v40, v38, v36, s[0:1]
	v_cndmask_b32_e64 v41, v39, v37, s[0:1]
	v_cndmask_b32_e64 v37, v37, v39, s[0:1]
	v_cndmask_b32_e64 v36, v36, v38, s[0:1]
	v_mov_b32_dpp v38, v40 row_ror:8 row_mask:0xf bank_mask:0xf bound_ctrl:1
	v_mov_b32_dpp v39, v41 row_ror:8 row_mask:0xf bank_mask:0xf bound_ctrl:1
	v_pk_add_f32 v[166:167], v[166:167], s[100:101] op_sel_hi:[1,0] neg_lo:[0,1] neg_hi:[0,1]
	s_nop 0
	v_pk_mul_f32 v[166:167], v[166:167], s[100:101] op_sel:[0,1]
	s_nop 0
	v_pk_fma_f32 v[166:167], v[246:247], v[166:167], v[248:249]
	s_nop 0
	v_pk_fma_f32 v[98:99], v[166:167], s[58:59], v[98:99] op_sel_hi:[1,0,1]
	v_pk_add_f32 v[36:37], v[36:37], v[38:39]
	s_mov_b32 s41, s7
	s_cmpk_eq_i32 s7, 0x100
	v_pk_add_f32 v[36:37], v[98:99], v[36:37]
	global_store_dwordx2 v[138:139], v[36:37], off nt
	s_cbranch_scc0 .LBB0_1139
	s_waitcnt vmcnt(0)
	s_barrier
	v_lshlrev_b64 v[0:1], 12, v[74:75]
	v_lshl_add_u64 v[0:1], s[60:61], 0, v[0:1]
	v_mov_b32_e32 v77, v73
	v_lshl_add_u64 v[64:65], v[0:1], 0, v[76:77]
	v_lshl_add_u64 v[66:67], s[90:91], 0, v[76:77]
	v_lshl_add_u64 v[68:69], s[68:69], 0, v[76:77]
	s_mov_b64 s[100:101], 0x1000
	v_lshl_add_u64 v[64:65], v[64:65], 0, s[100:101]
	global_load_dwordx4 v[206:209], v[66:67], off
	global_load_dwordx4 v[210:213], v[66:67], off offset:1024
	global_load_dwordx4 v[214:217], v[66:67], off offset:2048
	global_load_dwordx4 v[218:221], v[66:67], off offset:3072
	global_load_dwordx4 v[222:225], v[68:69], off
	global_load_dwordx4 v[226:229], v[68:69], off offset:1024
	global_load_dwordx4 v[230:233], v[68:69], off offset:2048
	global_load_dwordx4 v[234:237], v[68:69], off offset:3072
	global_load_dwordx4 v[0:3], v[64:65], off offset:-4096 nt
	global_load_dwordx4 v[4:7], v[64:65], off offset:-3072 nt
	global_load_dwordx4 v[8:11], v[64:65], off offset:-2048 nt
	global_load_dwordx4 v[12:15], v[64:65], off offset:-1024 nt
	global_load_dwordx4 v[40:43], v[66:67], off
	global_load_dwordx4 v[40:43], v[66:67], off
	global_load_dwordx4 v[40:43], v[66:67], off
	global_load_dwordx4 v[40:43], v[66:67], off
	s_mov_b32 s0, 0
.Lln2_pair:
	global_load_dwordx4 v[16:19], v[64:65], off nt
	global_load_dwordx4 v[20:23], v[64:65], off offset:1024 nt
	global_load_dwordx4 v[24:27], v[64:65], off offset:2048 nt
	global_load_dwordx4 v[28:31], v[64:65], off offset:3072 nt
	s_waitcnt vmcnt(8)
	v_pk_add_f32 v[32:33], v[0:1], v[2:3]
	v_pk_add_f32 v[34:35], v[4:5], v[6:7]
	v_pk_add_f32 v[36:37], v[8:9], v[10:11]
	v_pk_add_f32 v[38:39], v[12:13], v[14:15]
	v_pk_add_f32 v[32:33], v[32:33], v[34:35]
	v_pk_add_f32 v[36:37], v[36:37], v[38:39]
	s_nop 0
	v_pk_add_f32 v[32:33], v[32:33], v[36:37]
	s_nop 0
	v_add_f32_e32 v32, v32, v33
	s_nop 1
	v_add_f32_dpp v32, v32, v32 quad_perm:[1,0,3,2] row_mask:0xf bank_mask:0xf bound_ctrl:1
	s_nop 1
	v_add_f32_dpp v32, v32, v32 quad_perm:[2,3,0,1] row_mask:0xf bank_mask:0xf bound_ctrl:1
	s_nop 1
	v_add_f32_dpp v32, v32, v32 row_ror:4 row_mask:0xf bank_mask:0xf bound_ctrl:1
	s_nop 1
	v_add_f32_dpp v32, v32, v32 row_ror:8 row_mask:0xf bank_mask:0xf bound_ctrl:1
	s_nop 1
	v_add_f32_dpp v32, v32, v32 row_bcast:15 row_mask:0xa bank_mask:0xf
	s_nop 1
	v_add_f32_dpp v32, v32, v32 row_bcast:31 row_mask:0xc bank_mask:0xf
	s_nop 0
	v_readlane_b32 s98, v32, 63
	s_nop 1
	v_mov_b32_e32 v34, s98
	v_mul_f32_e32 v34, 0x3a800000, v34
	v_pk_add_f32 v[0:1], v[0:1], v[34:35] op_sel_hi:[1,0] neg_lo:[0,1] neg_hi:[0,1]
	v_pk_add_f32 v[2:3], v[2:3], v[34:35] op_sel_hi:[1,0] neg_lo:[0,1] neg_hi:[0,1]
	v_pk_add_f32 v[4:5], v[4:5], v[34:35] op_sel_hi:[1,0] neg_lo:[0,1] neg_hi:[0,1]
	v_pk_add_f32 v[6:7], v[6:7], v[34:35] op_sel_hi:[1,0] neg_lo:[0,1] neg_hi:[0,1]
	v_pk_add_f32 v[8:9], v[8:9], v[34:35] op_sel_hi:[1,0] neg_lo:[0,1] neg_hi:[0,1]
	v_pk_add_f32 v[10:11], v[10:11], v[34:35] op_sel_hi:[1,0] neg_lo:[0,1] neg_hi:[0,1]
	v_pk_add_f32 v[12:13], v[12:13], v[34:35] op_sel_hi:[1,0] neg_lo:[0,1] neg_hi:[0,1]
	v_pk_add_f32 v[14:15], v[14:15], v[34:35] op_sel_hi:[1,0] neg_lo:[0,1] neg_hi:[0,1]
	v_pk_mul_f32 v[36:37], v[0:1], v[0:1]
	v_pk_mul_f32 v[38:39], v[2:3], v[2:3]
	v_pk_fma_f32 v[36:37], v[4:5], v[4:5], v[36:37]
	v_pk_fma_f32 v[38:39], v[6:7], v[6:7], v[38:39]
	v_pk_fma_f32 v[36:37], v[8:9], v[8:9], v[36:37]
	v_pk_fma_f32 v[38:39], v[10:11], v[10:11], v[38:39]
	v_pk_fma_f32 v[36:37], v[12:13], v[12:13], v[36:37]
	v_pk_fma_f32 v[38:39], v[14:15], v[14:15], v[38:39]
	s_nop 0
	v_pk_add_f32 v[36:37], v[36:37], v[38:39]
	s_nop 0
	v_add_f32_e32 v36, v36, v37
	s_nop 1
	v_add_f32_dpp v36, v36, v36 quad_perm:[1,0,3,2] row_mask:0xf bank_mask:0xf bound_ctrl:1
	s_nop 1
	v_add_f32_dpp v36, v36, v36 quad_perm:[2,3,0,1] row_mask:0xf bank_mask:0xf bound_ctrl:1
	s_nop 1
	v_add_f32_dpp v36, v36, v36 row_ror:4 row_mask:0xf bank_mask:0xf bound_ctrl:1
	s_nop 1
	v_add_f32_dpp v36, v36, v36 row_ror:8 row_mask:0xf bank_mask:0xf bound_ctrl:1
	s_nop 1
	v_add_f32_dpp v36, v36, v36 row_bcast:15 row_mask:0xa bank_mask:0xf
	s_nop 1
	v_add_f32_dpp v36, v36, v36 row_bcast:31 row_mask:0xc bank_mask:0xf
	s_nop 0
	v_readlane_b32 s99, v36, 63
	s_nop 1
	v_mov_b32_e32 v38, s99
	v_fmamk_f32 v38, v38, 0x3a800000, v140
	v_rsq_f32_e32 v38, v38
	s_nop 0
	v_pk_mul_f32 v[0:1], v[0:1], v[38:39] op_sel_hi:[1,0]
	v_pk_mul_f32 v[2:3], v[2:3], v[38:39] op_sel_hi:[1,0]
	v_pk_mul_f32 v[4:5], v[4:5], v[38:39] op_sel_hi:[1,0]
	v_pk_mul_f32 v[6:7], v[6:7], v[38:39] op_sel_hi:[1,0]
	v_pk_mul_f32 v[8:9], v[8:9], v[38:39] op_sel_hi:[1,0]
	v_pk_mul_f32 v[10:11], v[10:11], v[38:39] op_sel_hi:[1,0]
	v_pk_mul_f32 v[12:13], v[12:13], v[38:39] op_sel_hi:[1,0]
	v_pk_mul_f32 v[14:15], v[14:15], v[38:39] op_sel_hi:[1,0]
	v_pk_fma_f32 v[0:1], v[206:207], v[0:1], v[222:223]
	v_pk_fma_f32 v[2:3], v[208:209], v[2:3], v[224:225]
	v_pk_fma_f32 v[4:5], v[210:211], v[4:5], v[226:227]
	v_pk_fma_f32 v[6:7], v[212:213], v[6:7], v[228:229]
	v_pk_fma_f32 v[8:9], v[214:215], v[8:9], v[230:231]
	v_pk_fma_f32 v[10:11], v[216:217], v[10:11], v[232:233]
	v_pk_fma_f32 v[12:13], v[218:219], v[12:13], v[234:235]
	v_pk_fma_f32 v[14:15], v[220:221], v[14:15], v[236:237]
	s_nop 0
	global_store_dwordx4 v[64:65], v[0:3], off offset:-4096 nt
	global_store_dwordx4 v[64:65], v[4:7], off offset:-3072 nt
	global_store_dwordx4 v[64:65], v[8:11], off offset:-2048 nt
	global_store_dwordx4 v[64:65], v[12:15], off offset:-1024 nt
	s_movk_i32 s100, 0x2000
	s_cmp_lt_u32 s0, 15
	s_cselect_b32 s100, s100, 0x1000
	s_mov_b32 s101, 0
	v_lshl_add_u64 v[58:59], v[64:65], 0, s[100:101]
	global_load_dwordx4 v[0:3], v[58:59], off offset:-4096 nt
	global_load_dwordx4 v[4:7], v[58:59], off offset:-3072 nt
	global_load_dwordx4 v[8:11], v[58:59], off offset:-2048 nt
	global_load_dwordx4 v[12:15], v[58:59], off offset:-1024 nt
	s_waitcnt vmcnt(8)
	v_pk_add_f32 v[32:33], v[16:17], v[18:19]
	v_pk_add_f32 v[34:35], v[20:21], v[22:23]
	v_pk_add_f32 v[36:37], v[24:25], v[26:27]
	v_pk_add_f32 v[38:39], v[28:29], v[30:31]
	v_pk_add_f32 v[32:33], v[32:33], v[34:35]
	v_pk_add_f32 v[36:37], v[36:37], v[38:39]
	s_nop 0
	v_pk_add_f32 v[32:33], v[32:33], v[36:37]
	s_nop 0
	v_add_f32_e32 v32, v32, v33
	s_nop 1
	v_add_f32_dpp v32, v32, v32 quad_perm:[1,0,3,2] row_mask:0xf bank_mask:0xf bound_ctrl:1
	s_nop 1
	v_add_f32_dpp v32, v32, v32 quad_perm:[2,3,0,1] row_mask:0xf bank_mask:0xf bound_ctrl:1
	s_nop 1
	v_add_f32_dpp v32, v32, v32 row_ror:4 row_mask:0xf bank_mask:0xf bound_ctrl:1
	s_nop 1
	v_add_f32_dpp v32, v32, v32 row_ror:8 row_mask:0xf bank_mask:0xf bound_ctrl:1
	s_nop 1
	v_add_f32_dpp v32, v32, v32 row_bcast:15 row_mask:0xa bank_mask:0xf
	s_nop 1
	v_add_f32_dpp v32, v32, v32 row_bcast:31 row_mask:0xc bank_mask:0xf
	s_nop 0
	v_readlane_b32 s98, v32, 63
	s_nop 1
	v_mov_b32_e32 v34, s98
	v_mul_f32_e32 v34, 0x3a800000, v34
	v_pk_add_f32 v[16:17], v[16:17], v[34:35] op_sel_hi:[1,0] neg_lo:[0,1] neg_hi:[0,1]
	v_pk_add_f32 v[18:19], v[18:19], v[34:35] op_sel_hi:[1,0] neg_lo:[0,1] neg_hi:[0,1]
	v_pk_add_f32 v[20:21], v[20:21], v[34:35] op_sel_hi:[1,0] neg_lo:[0,1] neg_hi:[0,1]
	v_pk_add_f32 v[22:23], v[22:23], v[34:35] op_sel_hi:[1,0] neg_lo:[0,1] neg_hi:[0,1]
	v_pk_add_f32 v[24:25], v[24:25], v[34:35] op_sel_hi:[1,0] neg_lo:[0,1] neg_hi:[0,1]
	v_pk_add_f32 v[26:27], v[26:27], v[34:35] op_sel_hi:[1,0] neg_lo:[0,1] neg_hi:[0,1]
	v_pk_add_f32 v[28:29], v[28:29], v[34:35] op_sel_hi:[1,0] neg_lo:[0,1] neg_hi:[0,1]
	v_pk_add_f32 v[30:31], v[30:31], v[34:35] op_sel_hi:[1,0] neg_lo:[0,1] neg_hi:[0,1]
	v_pk_mul_f32 v[36:37], v[16:17], v[16:17]
	v_pk_mul_f32 v[38:39], v[18:19], v[18:19]
	v_pk_fma_f32 v[36:37], v[20:21], v[20:21], v[36:37]
	v_pk_fma_f32 v[38:39], v[22:23], v[22:23], v[38:39]
	v_pk_fma_f32 v[36:37], v[24:25], v[24:25], v[36:37]
	v_pk_fma_f32 v[38:39], v[26:27], v[26:27], v[38:39]
	v_pk_fma_f32 v[36:37], v[28:29], v[28:29], v[36:37]
	v_pk_fma_f32 v[38:39], v[30:31], v[30:31], v[38:39]
	s_nop 0
	v_pk_add_f32 v[36:37], v[36:37], v[38:39]
	s_nop 0
	v_add_f32_e32 v36, v36, v37
	s_nop 1
	v_add_f32_dpp v36, v36, v36 quad_perm:[1,0,3,2] row_mask:0xf bank_mask:0xf bound_ctrl:1
	s_nop 1
	v_add_f32_dpp v36, v36, v36 quad_perm:[2,3,0,1] row_mask:0xf bank_mask:0xf bound_ctrl:1
	s_nop 1
	v_add_f32_dpp v36, v36, v36 row_ror:4 row_mask:0xf bank_mask:0xf bound_ctrl:1
	s_nop 1
	v_add_f32_dpp v36, v36, v36 row_ror:8 row_mask:0xf bank_mask:0xf bound_ctrl:1
	s_nop 1
	v_add_f32_dpp v36, v36, v36 row_bcast:15 row_mask:0xa bank_mask:0xf
	s_nop 1
	v_add_f32_dpp v36, v36, v36 row_bcast:31 row_mask:0xc bank_mask:0xf
	s_nop 0
	v_readlane_b32 s99, v36, 63
	s_nop 1
	v_mov_b32_e32 v38, s99
	v_fmamk_f32 v38, v38, 0x3a800000, v140
	v_rsq_f32_e32 v38, v38
	s_nop 0
	v_pk_mul_f32 v[16:17], v[16:17], v[38:39] op_sel_hi:[1,0]
	v_pk_mul_f32 v[18:19], v[18:19], v[38:39] op_sel_hi:[1,0]
	v_pk_mul_f32 v[20:21], v[20:21], v[38:39] op_sel_hi:[1,0]
	v_pk_mul_f32 v[22:23], v[22:23], v[38:39] op_sel_hi:[1,0]
	v_pk_mul_f32 v[24:25], v[24:25], v[38:39] op_sel_hi:[1,0]
	v_pk_mul_f32 v[26:27], v[26:27], v[38:39] op_sel_hi:[1,0]
	v_pk_mul_f32 v[28:29], v[28:29], v[38:39] op_sel_hi:[1,0]
	v_pk_mul_f32 v[30:31], v[30:31], v[38:39] op_sel_hi:[1,0]
	v_pk_fma_f32 v[16:17], v[206:207], v[16:17], v[222:223]
	v_pk_fma_f32 v[18:19], v[208:209], v[18:19], v[224:225]
	v_pk_fma_f32 v[20:21], v[210:211], v[20:21], v[226:227]
	v_pk_fma_f32 v[22:23], v[212:213], v[22:23], v[228:229]
	v_pk_fma_f32 v[24:25], v[214:215], v[24:25], v[230:231]
	v_pk_fma_f32 v[26:27], v[216:217], v[26:27], v[232:233]
	v_pk_fma_f32 v[28:29], v[218:219], v[28:29], v[234:235]
	v_pk_fma_f32 v[30:31], v[220:221], v[30:31], v[236:237]
	s_nop 0
	global_store_dwordx4 v[64:65], v[16:19], off nt
	global_store_dwordx4 v[64:65], v[20:23], off offset:1024 nt
	global_store_dwordx4 v[64:65], v[24:27], off offset:2048 nt
	global_store_dwordx4 v[64:65], v[28:31], off offset:3072 nt
	v_mov_b64_e32 v[64:65], v[58:59]
	s_add_i32 s0, s0, 1
	s_cmp_lg_u32 s0, 16
	s_cbranch_scc1 .Lln2_pair
	s_add_i32 s2, s2, s92
	s_add_i32 s10, s10, s23
	s_cmpk_gt_i32 s2, 0xff
	s_cbranch_scc0 .LBB0_1068
